# ATTB final-pass gate loads hoisted into the unit's last key-row step (latency under the last tile steps), next-unit Q loads unconditional; on top of v64
# speedup vs baseline: 1.0072x; 1.0007x over previous
; __device__ __forceinline__ void gate_load(v4u (&gw)[8], const bf16* grow, int tid) {
; #pragma unroll
;     for (int it = 0; it < 8; ++it) gw[it] = *(const v4u*)(grow + (size_t)((tid >> 3) + 64 * it) * 1024 + 8 * (tid & 7));
; }
; __device__ __forceinline__ void attn_b_phase(Frame& F, const float cshift, const bf16* qkv, const bf16* gate, bf16* y, const float* rpb, const float* qg, const float* kg) {
;     ...
;         const size_t tok0 = (size_t)cur.b * 4096 + 512 * R; const int h = cur.h;
;         int tidf = tid; asm volatile("" : "+v"(tidf));
;         v4u gw[8]; gate_load(gw, gate + tok0 * 1024 + h * 64, tidf);
.LBB0_650:
	s_add_i32 s100, s62, s63
	s_cmp_lg_u32 s100, -1
	s_cbranch_scc1 .Lgh_skip
	s_lshl_b32 s100, s20, 23
	s_lshl_b32 s32, s59, 20
	s_add_u32 s100, s100, s32
	s_lshl_b32 s32, s58, 7
	s_add_u32 s100, s100, s32
	s_add_u32 vcc_lo, s0, s100
	s_addc_u32 vcc_hi, s1, 0
	v_and_b32_e32 v244, 7, v190
	v_lshlrev_b32_e32 v244, 4, v244
	v_lshrrev_b32_e32 v245, 3, v190
	v_lshl_add_u32 v244, v245, 11, v244
	global_load_dwordx4 v[212:215], v244, vcc
	v_add_u32_e32 v244, 0x20000, v244
	global_load_dwordx4 v[216:219], v244, vcc
	v_add_u32_e32 v244, 0x20000, v244
	global_load_dwordx4 v[220:223], v244, vcc
	v_add_u32_e32 v244, 0x20000, v244
	global_load_dwordx4 v[224:227], v244, vcc
	v_add_u32_e32 v244, 0x20000, v244
	global_load_dwordx4 v[228:231], v244, vcc
	v_add_u32_e32 v244, 0x20000, v244
	global_load_dwordx4 v[232:235], v244, vcc
	v_add_u32_e32 v244, 0x20000, v244
	global_load_dwordx4 v[236:239], v244, vcc
	v_add_u32_e32 v244, 0x20000, v244
	global_load_dwordx4 v[240:243], v244, vcc

; #define ATT_QLOADB(U) do { const bf16* qa_ = qkv + ((size_t)((U).b * 16 + (U).h) * 4096 + 512 * (U).R + (2 * wq + (q >> 4)) * 64 + gcq) * 64; \
;         _Pragma("unroll") for (int d0 = 0; d0 < 4; ++d0) { st.qA[d0] = *(const bf16x8*)(qa_ + d0 * 16 + hi * 8); st.qB[d0] = *(const bf16x8*)(qa_ + 256 * 64 + d0 * 16 + hi * 8); } } while (0)
; __device__ __forceinline__ void attn_b_phase(Frame& F, const float cshift, const bf16* qkv, const bf16* gate, bf16* y, const float* rpb, const float* qg, const float* kg) {
;     ...
;         if (more) ATT_QLOADB(nxt);
.LBB0_655:
	s_add_i32 s55, s55, s63
	v_mov_b32_e32 v64, v177
	v_readlane_b32 s63, v252, 39
	s_and_b64 vcc, exec, s[24:25]
.LBB0_656:
	s_lshl_b32 s2, s45, 4
	s_add_i32 s24, s2, s44
	s_ashr_i32 s25, s24, 31
	s_lshl_b32 s12, s43, 9
	s_lshl_b64 s[24:25], s[24:25], 19
	v_lshl_add_u64 v[66:67], v[162:163], 0, s[12:13]
	s_add_u32 s24, s33, s24
	v_lshlrev_b64 v[66:67], 7, v[66:67]
	s_addc_u32 s25, s40, s25
	v_lshl_add_u64 v[66:67], s[24:25], 0, v[66:67]
	v_mov_b32_e32 v175, v147
	v_lshl_add_u64 v[66:67], v[66:67], 0, v[174:175]
	v_add_co_u32_e32 v70, vcc, 0x8000, v66
	v_lshl_add_u64 v[68:69], v[66:67], 0, s[16:17]
	s_nop 0
	v_addc_co_u32_e32 v71, vcc, 0, v67, vcc
	global_load_dwordx4 v[80:83], v[66:67], off
	global_load_dwordx4 v[84:87], v[66:67], off offset:32
	global_load_dwordx4 v[88:91], v[68:69], off offset:32
	global_load_dwordx4 v[92:95], v[68:69], off offset:64
	global_load_dwordx4 v[96:99], v[66:67], off offset:64
	global_load_dwordx4 v[100:103], v[66:67], off offset:96
	global_load_dwordx4 v[104:107], v[70:71], off
	global_load_dwordx4 v[108:111], v[68:69], off offset:96

; #define LAS __attribute__((address_space(3)))
; __device__ __forceinline__ unsigned cvtpk(float lo, float hi) { f32x2_t v = {lo, hi}; bf16x2_t b = __builtin_convertvector(v, bf16x2_t); return __builtin_bit_cast(unsigned, b); }
; template <bool NT = false>
; __device__ __forceinline__ void final_store(const v4u (&gw)[8], LAS char* lds, bf16* yrow, int tid) {
; #pragma unroll
;     for (int it = 0; it < 8; ++it) {
;         const int tloc = (tid >> 3) + 64 * it, c = tid & 7;
;         const LAS char* row = lds + ACC_OFF + rho(tloc) * ACC_PITCH + 16 * c;
;         const v2u a0 = *(const LAS v2u*)row, a1 = *(const LAS v2u*)(row + 8);
;         const float inv = __builtin_amdgcn_rcpf(*((const LAS float*)(lds + LACC_OFF) + tloc));
;         v4u g = gw[it];
;         float gs[8];
;         { const unsigned gu[4] = {g.x, g.y, g.z, g.w};
; #pragma unroll
;           for (int k = 0; k < 4; ++k) { const float a = __builtin_bit_cast(float, gu[k] << 16), b = __builtin_bit_cast(float, gu[k] & 0xffff0000u);
;               gs[2 * k] = a * __builtin_amdgcn_rcpf(1.0f + __builtin_amdgcn_exp2f(-LOG2E * a)); gs[2 * k + 1] = b * __builtin_amdgcn_rcpf(1.0f + __builtin_amdgcn_exp2f(-LOG2E * b)); } }
;         v4u w;
;         w.x = cvtpk(__builtin_bit_cast(float, a0.x << 16) * inv * gs[0], __builtin_bit_cast(float, a0.x & 0xffff0000u) * inv * gs[1]);
;         w.y = cvtpk(__builtin_bit_cast(float, a0.y << 16) * inv * gs[2], __builtin_bit_cast(float, a0.y & 0xffff0000u) * inv * gs[3]);
;         w.z = cvtpk(__builtin_bit_cast(float, a1.x << 16) * inv * gs[4], __builtin_bit_cast(float, a1.x & 0xffff0000u) * inv * gs[5]);
;         w.w = cvtpk(__builtin_bit_cast(float, a1.y << 16) * inv * gs[6], __builtin_bit_cast(float, a1.y & 0xffff0000u) * inv * gs[7]);
;         if (NT) __builtin_nontemporal_store(w, (v4u*)(yrow + (size_t)tloc * 1024 + 8 * c)); else *(v4u*)(yrow + (size_t)tloc * 1024 + 8 * c) = w;
; __device__ __forceinline__ void attn_b_phase(Frame& F, const float cshift, const bf16* qkv, const bf16* gate, bf16* y, const float* rpb, const float* qg, const float* kg) {
;     ...
;         const size_t tok0 = (size_t)cur.b * 4096 + 512 * R; const int h = cur.h;
;         int tidf = tid; asm volatile("" : "+v"(tidf));
;         v4u gw[8]; gate_load(gw, gate + tok0 * 1024 + h * 64, tidf);
;         ATT_BAR();
;         final_store(gw, lds, y + tok0 * 1024 + h * 64, tidf);
.LBB0_666:
	s_or_b64 exec, exec, s[22:23]
	s_ashr_i32 s21, s20, 31
	s_lshl_b32 s12, s59, 9
	s_lshl_b64 s[20:21], s[20:21], 22
	s_lshl_b64 s[22:23], s[12:13], 10
	s_add_u32 s20, s22, s20
	s_addc_u32 s21, s23, s21
	s_lshl_b64 s[20:21], s[20:21], 1
	v_mov_b32_e32 v0, v190
	s_add_u32 s2, s0, s20
	s_addc_u32 s12, s1, s21
	s_lshl_b32 s24, s58, 7
	s_add_u32 s22, s2, s24
	v_ashrrev_i32_e32 v70, 3, v0
	v_lshlrev_b32_e32 v0, 4, v0
	s_addc_u32 s23, s12, 0
	v_and_b32_e32 v146, 0x70, v0
	v_ashrrev_i32_e32 v71, 31, v70
	v_lshl_add_u64 v[0:1], s[22:23], 0, v[146:147]
	v_lshlrev_b64 v[62:63], 11, v[70:71]
	v_lshl_add_u64 v[2:3], v[0:1], 0, v[62:63]
	v_add_u32_e32 v64, 64, v70
	v_ashrrev_i32_e32 v65, 31, v64
	v_lshlrev_b64 v[58:59], 11, v[64:65]
	v_lshl_add_u64 v[2:3], v[0:1], 0, v[58:59]
	v_add_u32_e32 v60, 0x80, v70
	v_ashrrev_i32_e32 v61, 31, v60
	v_add_u32_e32 v56, 0xc0, v70
	v_lshlrev_b64 v[54:55], 11, v[60:61]
	v_ashrrev_i32_e32 v57, 31, v56
	v_add_u32_e32 v52, 0x100, v70
	v_lshl_add_u64 v[2:3], v[0:1], 0, v[54:55]
	v_lshlrev_b64 v[50:51], 11, v[56:57]
	v_ashrrev_i32_e32 v53, 31, v52
	v_add_u32_e32 v48, 0x140, v70
	v_add_u32_e32 v38, 0x1c0, v70
	s_add_u32 s2, s63, s20
	v_lshl_add_u64 v[2:3], v[0:1], 0, v[50:51]
	v_lshlrev_b64 v[46:47], 11, v[52:53]
	v_ashrrev_i32_e32 v49, 31, v48
	v_add_u32_e32 v44, 0x180, v70
	v_ashrrev_i32_e32 v39, 31, v38
	s_addc_u32 s12, s64, s21
	v_lshl_add_u64 v[2:3], v[0:1], 0, v[46:47]
	v_lshlrev_b64 v[42:43], 11, v[48:49]
	v_ashrrev_i32_e32 v45, 31, v44
	v_lshlrev_b64 v[32:33], 11, v[38:39]
	s_add_u32 s20, s2, s24
	v_lshrrev_b32_e32 v39, 5, v70
	v_lshl_add_u64 v[2:3], v[0:1], 0, v[42:43]
	v_lshlrev_b64 v[36:37], 11, v[44:45]
	s_addc_u32 s21, s12, 0
	v_add_u32_e32 v40, 0, v146
	v_bitop3_b32 v39, v39, v70, 15 bitop3:0x6c
	v_lshl_add_u64 v[2:3], v[0:1], 0, v[36:37]
	v_lshl_add_u64 v[0:1], v[0:1], 0, v[32:33]
	v_lshl_add_u64 v[34:35], s[20:21], 0, v[146:147]
	v_mad_u64_u32 v[66:67], s[20:21], v39, s52, v[40:41]
	v_lshl_add_u32 v39, v70, 2, 0
	v_add_u32_e32 v39, 0x11000, v39
	s_waitcnt lgkmcnt(0)
	s_barrier
	ds_read2st64_b32 v[70:71], v39 offset1:1
	ds_read2_b64 v[66:69], v66 offset1:1
	v_lshl_add_u64 v[62:63], v[34:35], 0, v[62:63]
	s_add_i32 s2, s57, 2
	s_cmp_ge_i32 s2, s42
	s_waitcnt lgkmcnt(1)
	v_rcp_f32_e32 v70, v70
	s_mov_b32 s2, s43
	s_mov_b32 s38, s48
	s_mov_b64 s[24:25], s[10:11]
	s_mov_b64 s[22:23], s[8:9]
	s_mov_b32 s12, s44
	s_mov_b32 s39, s45
	s_waitcnt vmcnt(15)
	v_mov_b32_e32 v28, v212
	v_mov_b32_e32 v29, v213
	v_mov_b32_e32 v30, v214
	v_mov_b32_e32 v31, v215
	v_lshlrev_b32_e32 v72, 16, v28
	v_and_b32_e32 v73, 0xffff0000, v28
	v_mul_f32_e32 v28, 0xbfb8aa3b, v72
	v_exp_f32_e32 v28, v28
	s_waitcnt vmcnt(14)
	v_mov_b32_e32 v24, v216
	v_mov_b32_e32 v25, v217
	v_mov_b32_e32 v26, v218
	v_mov_b32_e32 v27, v219
	v_and_b32_e32 v65, 0xffff0000, v24
	v_add_f32_e32 v28, 1.0, v28
	v_rcp_f32_e32 v74, v28
	v_mul_f32_e32 v28, 0xbfb8aa3b, v73
	v_exp_f32_e32 v28, v28
	s_nop 0
	v_add_f32_e32 v28, 1.0, v28
	v_rcp_f32_e32 v75, v28
	s_nop 0
	v_pk_mul_f32 v[72:73], v[74:75], v[72:73]
	s_waitcnt lgkmcnt(0)
	v_lshlrev_b32_e32 v74, 16, v66
	v_and_b32_e32 v75, 0xffff0000, v66
	v_pk_mul_f32 v[74:75], v[70:71], v[74:75] op_sel_hi:[0,1]
	v_pk_mul_f32 v[72:73], v[72:73], v[74:75]
	v_lshlrev_b32_e32 v66, 16, v67
	v_cvt_pk_bf16_f32 v28, v72, v73
	v_lshlrev_b32_e32 v72, 16, v29
	v_and_b32_e32 v73, 0xffff0000, v29
	v_mul_f32_e32 v29, 0xbfb8aa3b, v72
	v_exp_f32_e32 v29, v29
	v_and_b32_e32 v67, 0xffff0000, v67
	v_pk_mul_f32 v[66:67], v[70:71], v[66:67] op_sel_hi:[0,1]
	v_add_f32_e32 v29, 1.0, v29
	v_rcp_f32_e32 v74, v29
	v_mul_f32_e32 v29, 0xbfb8aa3b, v73
	v_exp_f32_e32 v29, v29
	s_nop 0
	v_add_f32_e32 v29, 1.0, v29
	v_rcp_f32_e32 v75, v29
	s_nop 0
	v_pk_mul_f32 v[72:73], v[74:75], v[72:73]
	s_nop 0
	v_pk_mul_f32 v[66:67], v[72:73], v[66:67]
	s_nop 0
	v_cvt_pk_bf16_f32 v29, v66, v67
	v_lshlrev_b32_e32 v66, 16, v30
	v_and_b32_e32 v67, 0xffff0000, v30
	v_mul_f32_e32 v30, 0xbfb8aa3b, v66
	v_exp_f32_e32 v30, v30
	s_nop 0
	v_add_f32_e32 v30, 1.0, v30
	v_rcp_f32_e32 v72, v30
	v_mul_f32_e32 v30, 0xbfb8aa3b, v67
	v_exp_f32_e32 v30, v30
	s_nop 0
	v_add_f32_e32 v30, 1.0, v30
	v_rcp_f32_e32 v73, v30
	s_nop 0
	v_pk_mul_f32 v[66:67], v[72:73], v[66:67]
	v_lshlrev_b32_e32 v72, 16, v68
	v_and_b32_e32 v73, 0xffff0000, v68
	v_pk_mul_f32 v[72:73], v[70:71], v[72:73] op_sel_hi:[0,1]
	v_pk_mul_f32 v[66:67], v[66:67], v[72:73]
	v_lshlrev_b32_e32 v68, 16, v69
	v_cvt_pk_bf16_f32 v30, v66, v67
	v_lshlrev_b32_e32 v66, 16, v31
	v_and_b32_e32 v67, 0xffff0000, v31
	v_mul_f32_e32 v31, 0xbfb8aa3b, v66
	v_exp_f32_e32 v31, v31
	v_and_b32_e32 v69, 0xffff0000, v69
	v_pk_mul_f32 v[68:69], v[70:71], v[68:69] op_sel_hi:[0,1]
	v_add_f32_e32 v31, 1.0, v31
	v_rcp_f32_e32 v72, v31
	v_mul_f32_e32 v31, 0xbfb8aa3b, v67
	v_exp_f32_e32 v31, v31
	s_nop 0
	v_add_f32_e32 v31, 1.0, v31
	v_rcp_f32_e32 v73, v31
	s_nop 0
	v_pk_mul_f32 v[66:67], v[72:73], v[66:67]
	s_nop 0
	v_pk_mul_f32 v[66:67], v[66:67], v[68:69]
	s_nop 0
	v_cvt_pk_bf16_f32 v31, v66, v67
	global_store_dwordx4 v[62:63], v[28:31], off
	v_rcp_f32_e32 v62, v71
	s_nop 0
	v_lshrrev_b32_e32 v28, 5, v64
	v_bitop3_b32 v28, v28, v64, 15 bitop3:0x6c
	v_lshlrev_b32_e32 v64, 16, v24
	v_mul_f32_e32 v24, 0xbfb8aa3b, v64
	v_exp_f32_e32 v24, v24
	v_mad_u64_u32 v[28:29], s[20:21], v28, s52, v[40:41]
	ds_read2_b64 v[28:31], v28 offset1:1
	v_add_f32_e32 v24, 1.0, v24
	v_rcp_f32_e32 v66, v24
	v_mul_f32_e32 v24, 0xbfb8aa3b, v65
	v_exp_f32_e32 v24, v24
	s_nop 0
	v_add_f32_e32 v24, 1.0, v24
	v_rcp_f32_e32 v67, v24
	s_nop 0
	v_pk_mul_f32 v[64:65], v[66:67], v[64:65]
	s_waitcnt lgkmcnt(0)
; #define LAS __attribute__((address_space(3)))
; __device__ __forceinline__ unsigned cvtpk(float lo, float hi) { f32x2_t v = {lo, hi}; bf16x2_t b = __builtin_convertvector(v, bf16x2_t); return __builtin_bit_cast(unsigned, b); }
; template <bool NT = false>
; __device__ __forceinline__ void final_store(const v4u (&gw)[8], LAS char* lds, bf16* yrow, int tid) {
; #pragma unroll
;     for (int it = 0; it < 8; ++it) {
;         const int tloc = (tid >> 3) + 64 * it, c = tid & 7;
;         const LAS char* row = lds + ACC_OFF + rho(tloc) * ACC_PITCH + 16 * c;
;         const v2u a0 = *(const LAS v2u*)row, a1 = *(const LAS v2u*)(row + 8);
;         const float inv = __builtin_amdgcn_rcpf(*((const LAS float*)(lds + LACC_OFF) + tloc));
;         v4u g = gw[it];
;         float gs[8];
;         { const unsigned gu[4] = {g.x, g.y, g.z, g.w};
; #pragma unroll
;           for (int k = 0; k < 4; ++k) { const float a = __builtin_bit_cast(float, gu[k] << 16), b = __builtin_bit_cast(float, gu[k] & 0xffff0000u);
;               gs[2 * k] = a * __builtin_amdgcn_rcpf(1.0f + __builtin_amdgcn_exp2f(-LOG2E * a)); gs[2 * k + 1] = b * __builtin_amdgcn_rcpf(1.0f + __builtin_amdgcn_exp2f(-LOG2E * b)); } }
;         v4u w;
;         w.x = cvtpk(__builtin_bit_cast(float, a0.x << 16) * inv * gs[0], __builtin_bit_cast(float, a0.x & 0xffff0000u) * inv * gs[1]);
;         w.y = cvtpk(__builtin_bit_cast(float, a0.y << 16) * inv * gs[2], __builtin_bit_cast(float, a0.y & 0xffff0000u) * inv * gs[3]);
;         w.z = cvtpk(__builtin_bit_cast(float, a1.x << 16) * inv * gs[4], __builtin_bit_cast(float, a1.x & 0xffff0000u) * inv * gs[5]);
;         w.w = cvtpk(__builtin_bit_cast(float, a1.y << 16) * inv * gs[6], __builtin_bit_cast(float, a1.y & 0xffff0000u) * inv * gs[7]);
;         if (NT) __builtin_nontemporal_store(w, (v4u*)(yrow + (size_t)tloc * 1024 + 8 * c)); else *(v4u*)(yrow + (size_t)tloc * 1024 + 8 * c) = w;
	v_lshlrev_b32_e32 v66, 16, v28
	v_and_b32_e32 v67, 0xffff0000, v28
	v_pk_mul_f32 v[66:67], v[62:63], v[66:67] op_sel_hi:[0,1]
	v_pk_mul_f32 v[64:65], v[64:65], v[66:67]
	v_lshlrev_b32_e32 v28, 16, v29
	v_cvt_pk_bf16_f32 v24, v64, v65
	v_lshlrev_b32_e32 v64, 16, v25
	v_and_b32_e32 v65, 0xffff0000, v25
	v_mul_f32_e32 v25, 0xbfb8aa3b, v64
	v_exp_f32_e32 v25, v25
	v_and_b32_e32 v29, 0xffff0000, v29
	v_pk_mul_f32 v[28:29], v[62:63], v[28:29] op_sel_hi:[0,1]
	v_add_f32_e32 v25, 1.0, v25
	v_rcp_f32_e32 v66, v25
	v_mul_f32_e32 v25, 0xbfb8aa3b, v65
	v_exp_f32_e32 v25, v25
	s_nop 0
	v_add_f32_e32 v25, 1.0, v25
	v_rcp_f32_e32 v67, v25
	s_nop 0
	v_pk_mul_f32 v[64:65], v[66:67], v[64:65]
	s_nop 0
	v_pk_mul_f32 v[28:29], v[64:65], v[28:29]
	s_nop 0
	v_cvt_pk_bf16_f32 v25, v28, v29
	v_lshlrev_b32_e32 v28, 16, v26
	v_and_b32_e32 v29, 0xffff0000, v26
	v_mul_f32_e32 v26, 0xbfb8aa3b, v28
	v_exp_f32_e32 v26, v26
	s_nop 0
	v_add_f32_e32 v26, 1.0, v26
	v_rcp_f32_e32 v64, v26
	v_mul_f32_e32 v26, 0xbfb8aa3b, v29
	v_exp_f32_e32 v26, v26
	s_nop 0
	v_add_f32_e32 v26, 1.0, v26
	v_rcp_f32_e32 v65, v26
	s_nop 0
	v_pk_mul_f32 v[28:29], v[64:65], v[28:29]
	v_lshlrev_b32_e32 v64, 16, v30
	v_and_b32_e32 v65, 0xffff0000, v30
	v_pk_mul_f32 v[64:65], v[62:63], v[64:65] op_sel_hi:[0,1]
	v_pk_mul_f32 v[28:29], v[28:29], v[64:65]
	v_lshlrev_b32_e32 v30, 16, v31
	v_cvt_pk_bf16_f32 v26, v28, v29
	v_lshlrev_b32_e32 v28, 16, v27
	v_and_b32_e32 v29, 0xffff0000, v27
	v_mul_f32_e32 v27, 0xbfb8aa3b, v28
	v_exp_f32_e32 v27, v27
	v_and_b32_e32 v31, 0xffff0000, v31
	v_pk_mul_f32 v[30:31], v[62:63], v[30:31] op_sel_hi:[0,1]
	v_add_f32_e32 v27, 1.0, v27
	v_rcp_f32_e32 v64, v27
	v_mul_f32_e32 v27, 0xbfb8aa3b, v29
	v_exp_f32_e32 v27, v27
	s_nop 0
	v_add_f32_e32 v27, 1.0, v27
	v_rcp_f32_e32 v65, v27
	s_nop 0
	v_pk_mul_f32 v[28:29], v[64:65], v[28:29]
	s_nop 0
	v_pk_mul_f32 v[28:29], v[28:29], v[30:31]
	s_waitcnt vmcnt(14)
	v_mov_b32_e32 v20, v220
	v_mov_b32_e32 v21, v221
	v_mov_b32_e32 v22, v222
	v_mov_b32_e32 v23, v223
	v_lshlrev_b32_e32 v30, 16, v20
	v_and_b32_e32 v31, 0xffff0000, v20
	v_mul_f32_e32 v20, 0xbfb8aa3b, v30
	v_exp_f32_e32 v20, v20
	v_cvt_pk_bf16_f32 v27, v28, v29
	v_lshl_add_u64 v[28:29], v[34:35], 0, v[58:59]
	global_store_dwordx4 v[28:29], v[24:27], off
	v_add_f32_e32 v20, 1.0, v20
	v_rcp_f32_e32 v58, v20
	v_lshrrev_b32_e32 v24, 5, v60
	v_bitop3_b32 v24, v24, v60, 15 bitop3:0x6c
	v_mul_f32_e32 v20, 0xbfb8aa3b, v31
	v_mad_u64_u32 v[24:25], s[20:21], v24, s52, v[40:41]
	v_exp_f32_e32 v20, v20
	ds_read2_b64 v[24:27], v24 offset1:1
	ds_read2st64_b32 v[28:29], v39 offset0:2 offset1:3
	v_add_f32_e32 v20, 1.0, v20
	v_rcp_f32_e32 v59, v20
	s_waitcnt lgkmcnt(0)
	v_rcp_f32_e32 v28, v28
	v_pk_mul_f32 v[30:31], v[58:59], v[30:31]
	v_lshlrev_b32_e32 v58, 16, v24
	v_and_b32_e32 v59, 0xffff0000, v24
	v_pk_mul_f32 v[58:59], v[28:29], v[58:59] op_sel_hi:[0,1]
	v_pk_mul_f32 v[30:31], v[30:31], v[58:59]
	v_lshlrev_b32_e32 v24, 16, v25
	v_cvt_pk_bf16_f32 v20, v30, v31
	v_lshlrev_b32_e32 v30, 16, v21
	v_and_b32_e32 v31, 0xffff0000, v21
	v_mul_f32_e32 v21, 0xbfb8aa3b, v30
	v_exp_f32_e32 v21, v21
	v_and_b32_e32 v25, 0xffff0000, v25
	v_pk_mul_f32 v[24:25], v[28:29], v[24:25] op_sel_hi:[0,1]
	v_add_f32_e32 v21, 1.0, v21
	v_rcp_f32_e32 v58, v21
	v_mul_f32_e32 v21, 0xbfb8aa3b, v31
	v_exp_f32_e32 v21, v21
	s_nop 0
	v_add_f32_e32 v21, 1.0, v21
	v_rcp_f32_e32 v59, v21
	s_nop 0
	v_pk_mul_f32 v[30:31], v[58:59], v[30:31]
	s_nop 0
	v_pk_mul_f32 v[24:25], v[30:31], v[24:25]
	s_nop 0
	v_cvt_pk_bf16_f32 v21, v24, v25
	v_lshlrev_b32_e32 v24, 16, v22
	v_and_b32_e32 v25, 0xffff0000, v22
	v_mul_f32_e32 v22, 0xbfb8aa3b, v24
	v_exp_f32_e32 v22, v22
	s_nop 0
	v_add_f32_e32 v22, 1.0, v22
	v_rcp_f32_e32 v30, v22
	v_mul_f32_e32 v22, 0xbfb8aa3b, v25
	v_exp_f32_e32 v22, v22
	s_nop 0
	v_add_f32_e32 v22, 1.0, v22
	v_rcp_f32_e32 v31, v22
	s_nop 0
	v_pk_mul_f32 v[24:25], v[30:31], v[24:25]
	v_lshlrev_b32_e32 v30, 16, v26
	v_and_b32_e32 v31, 0xffff0000, v26
	v_pk_mul_f32 v[30:31], v[28:29], v[30:31] op_sel_hi:[0,1]
	v_pk_mul_f32 v[24:25], v[24:25], v[30:31]
	v_lshlrev_b32_e32 v26, 16, v27
	v_cvt_pk_bf16_f32 v22, v24, v25
	v_lshlrev_b32_e32 v24, 16, v23
	v_and_b32_e32 v25, 0xffff0000, v23
	v_mul_f32_e32 v23, 0xbfb8aa3b, v24
	v_exp_f32_e32 v23, v23
	v_and_b32_e32 v27, 0xffff0000, v27
	v_pk_mul_f32 v[26:27], v[28:29], v[26:27] op_sel_hi:[0,1]
	v_add_f32_e32 v23, 1.0, v23
	v_rcp_f32_e32 v30, v23
	v_mul_f32_e32 v23, 0xbfb8aa3b, v25
	v_exp_f32_e32 v23, v23
	s_nop 0
	v_add_f32_e32 v23, 1.0, v23
	v_rcp_f32_e32 v31, v23
	s_nop 0
	v_pk_mul_f32 v[24:25], v[30:31], v[24:25]
	s_nop 0
	v_pk_mul_f32 v[24:25], v[24:25], v[26:27]
	s_waitcnt vmcnt(14)
	v_mov_b32_e32 v16, v224
	v_mov_b32_e32 v17, v225
	v_mov_b32_e32 v18, v226
	v_mov_b32_e32 v19, v227
	v_lshlrev_b32_e32 v26, 16, v16
	v_and_b32_e32 v27, 0xffff0000, v16
	v_mul_f32_e32 v16, 0xbfb8aa3b, v26
	v_exp_f32_e32 v16, v16
	v_cvt_pk_bf16_f32 v23, v24, v25
	v_lshl_add_u64 v[24:25], v[34:35], 0, v[54:55]
	global_store_dwordx4 v[24:25], v[20:23], off
	v_add_f32_e32 v16, 1.0, v16
	v_rcp_f32_e32 v28, v16
	v_mul_f32_e32 v16, 0xbfb8aa3b, v27
	v_exp_f32_e32 v16, v16
	v_lshrrev_b32_e32 v20, 5, v56
	v_bitop3_b32 v20, v20, v56, 15 bitop3:0x6c
	v_mad_u64_u32 v[20:21], s[20:21], v20, s52, v[40:41]
	ds_read2_b64 v[20:23], v20 offset1:1
	v_add_f32_e32 v16, 1.0, v16
	v_rcp_f32_e32 v24, v29
	v_rcp_f32_e32 v29, v16
	s_nop 0
	v_pk_mul_f32 v[26:27], v[28:29], v[26:27]
	s_waitcnt lgkmcnt(0)
; #define LAS __attribute__((address_space(3)))
; __device__ __forceinline__ unsigned cvtpk(float lo, float hi) { f32x2_t v = {lo, hi}; bf16x2_t b = __builtin_convertvector(v, bf16x2_t); return __builtin_bit_cast(unsigned, b); }
; template <bool NT = false>
; __device__ __forceinline__ void final_store(const v4u (&gw)[8], LAS char* lds, bf16* yrow, int tid) {
; #pragma unroll
;     for (int it = 0; it < 8; ++it) {
;         const int tloc = (tid >> 3) + 64 * it, c = tid & 7;
;         const LAS char* row = lds + ACC_OFF + rho(tloc) * ACC_PITCH + 16 * c;
;         const v2u a0 = *(const LAS v2u*)row, a1 = *(const LAS v2u*)(row + 8);
;         const float inv = __builtin_amdgcn_rcpf(*((const LAS float*)(lds + LACC_OFF) + tloc));
;         v4u g = gw[it];
;         float gs[8];
;         { const unsigned gu[4] = {g.x, g.y, g.z, g.w};
; #pragma unroll
;           for (int k = 0; k < 4; ++k) { const float a = __builtin_bit_cast(float, gu[k] << 16), b = __builtin_bit_cast(float, gu[k] & 0xffff0000u);
;               gs[2 * k] = a * __builtin_amdgcn_rcpf(1.0f + __builtin_amdgcn_exp2f(-LOG2E * a)); gs[2 * k + 1] = b * __builtin_amdgcn_rcpf(1.0f + __builtin_amdgcn_exp2f(-LOG2E * b)); } }
;         v4u w;
;         w.x = cvtpk(__builtin_bit_cast(float, a0.x << 16) * inv * gs[0], __builtin_bit_cast(float, a0.x & 0xffff0000u) * inv * gs[1]);
;         w.y = cvtpk(__builtin_bit_cast(float, a0.y << 16) * inv * gs[2], __builtin_bit_cast(float, a0.y & 0xffff0000u) * inv * gs[3]);
;         w.z = cvtpk(__builtin_bit_cast(float, a1.x << 16) * inv * gs[4], __builtin_bit_cast(float, a1.x & 0xffff0000u) * inv * gs[5]);
;         w.w = cvtpk(__builtin_bit_cast(float, a1.y << 16) * inv * gs[6], __builtin_bit_cast(float, a1.y & 0xffff0000u) * inv * gs[7]);
;         if (NT) __builtin_nontemporal_store(w, (v4u*)(yrow + (size_t)tloc * 1024 + 8 * c)); else *(v4u*)(yrow + (size_t)tloc * 1024 + 8 * c) = w;
	v_lshlrev_b32_e32 v28, 16, v20
	v_and_b32_e32 v29, 0xffff0000, v20
	v_pk_mul_f32 v[28:29], v[24:25], v[28:29] op_sel_hi:[0,1]
	v_pk_mul_f32 v[26:27], v[26:27], v[28:29]
	v_lshlrev_b32_e32 v20, 16, v21
	v_cvt_pk_bf16_f32 v16, v26, v27
	v_lshlrev_b32_e32 v26, 16, v17
	v_and_b32_e32 v27, 0xffff0000, v17
	v_mul_f32_e32 v17, 0xbfb8aa3b, v26
	v_exp_f32_e32 v17, v17
	v_and_b32_e32 v21, 0xffff0000, v21
	v_pk_mul_f32 v[20:21], v[24:25], v[20:21] op_sel_hi:[0,1]
	v_add_f32_e32 v17, 1.0, v17
	v_rcp_f32_e32 v28, v17
	v_mul_f32_e32 v17, 0xbfb8aa3b, v27
	v_exp_f32_e32 v17, v17
	s_nop 0
	v_add_f32_e32 v17, 1.0, v17
	v_rcp_f32_e32 v29, v17
	s_nop 0
	v_pk_mul_f32 v[26:27], v[28:29], v[26:27]
	s_nop 0
	v_pk_mul_f32 v[20:21], v[26:27], v[20:21]
	s_nop 0
	v_cvt_pk_bf16_f32 v17, v20, v21
	v_lshlrev_b32_e32 v20, 16, v18
	v_and_b32_e32 v21, 0xffff0000, v18
	v_mul_f32_e32 v18, 0xbfb8aa3b, v20
	v_exp_f32_e32 v18, v18
	s_nop 0
	v_add_f32_e32 v18, 1.0, v18
	v_rcp_f32_e32 v26, v18
	v_mul_f32_e32 v18, 0xbfb8aa3b, v21
	v_exp_f32_e32 v18, v18
	s_nop 0
	v_add_f32_e32 v18, 1.0, v18
	v_rcp_f32_e32 v27, v18
	s_nop 0
	v_pk_mul_f32 v[20:21], v[26:27], v[20:21]
	v_lshlrev_b32_e32 v26, 16, v22
	v_and_b32_e32 v27, 0xffff0000, v22
	v_pk_mul_f32 v[26:27], v[24:25], v[26:27] op_sel_hi:[0,1]
	v_pk_mul_f32 v[20:21], v[20:21], v[26:27]
	v_lshlrev_b32_e32 v22, 16, v23
	v_cvt_pk_bf16_f32 v18, v20, v21
	v_lshlrev_b32_e32 v20, 16, v19
	v_and_b32_e32 v21, 0xffff0000, v19
	v_mul_f32_e32 v19, 0xbfb8aa3b, v20
	v_exp_f32_e32 v19, v19
	v_and_b32_e32 v23, 0xffff0000, v23
	v_pk_mul_f32 v[22:23], v[24:25], v[22:23] op_sel_hi:[0,1]
	v_add_f32_e32 v19, 1.0, v19
	v_rcp_f32_e32 v26, v19
	v_mul_f32_e32 v19, 0xbfb8aa3b, v21
	v_exp_f32_e32 v19, v19
	s_nop 0
	v_add_f32_e32 v19, 1.0, v19
	v_rcp_f32_e32 v27, v19
	s_nop 0
	v_pk_mul_f32 v[20:21], v[26:27], v[20:21]
	s_nop 0
	v_pk_mul_f32 v[20:21], v[20:21], v[22:23]
	s_waitcnt vmcnt(14)
	v_mov_b32_e32 v12, v228
	v_mov_b32_e32 v13, v229
	v_mov_b32_e32 v14, v230
	v_mov_b32_e32 v15, v231
	v_lshlrev_b32_e32 v22, 16, v12
	v_and_b32_e32 v23, 0xffff0000, v12
	v_mul_f32_e32 v12, 0xbfb8aa3b, v22
	v_exp_f32_e32 v12, v12
	v_cvt_pk_bf16_f32 v19, v20, v21
	v_lshl_add_u64 v[20:21], v[34:35], 0, v[50:51]
	global_store_dwordx4 v[20:21], v[16:19], off
	v_add_f32_e32 v12, 1.0, v12
	v_rcp_f32_e32 v24, v12
	v_lshrrev_b32_e32 v16, 5, v52
	v_bitop3_b32 v16, v16, v52, 15 bitop3:0x6c
	v_mul_f32_e32 v12, 0xbfb8aa3b, v23
	v_mad_u64_u32 v[16:17], s[20:21], v16, s52, v[40:41]
	v_exp_f32_e32 v12, v12
	ds_read2_b64 v[16:19], v16 offset1:1
	ds_read2st64_b32 v[20:21], v39 offset0:4 offset1:5
	v_add_f32_e32 v12, 1.0, v12
	v_rcp_f32_e32 v25, v12
	s_waitcnt lgkmcnt(0)
	v_rcp_f32_e32 v20, v20
	v_pk_mul_f32 v[22:23], v[24:25], v[22:23]
	v_lshlrev_b32_e32 v24, 16, v16
	v_and_b32_e32 v25, 0xffff0000, v16
	v_pk_mul_f32 v[24:25], v[20:21], v[24:25] op_sel_hi:[0,1]
	v_pk_mul_f32 v[22:23], v[22:23], v[24:25]
	v_lshlrev_b32_e32 v16, 16, v17
	v_cvt_pk_bf16_f32 v12, v22, v23
	v_lshlrev_b32_e32 v22, 16, v13
	v_and_b32_e32 v23, 0xffff0000, v13
	v_mul_f32_e32 v13, 0xbfb8aa3b, v22
	v_exp_f32_e32 v13, v13
	v_and_b32_e32 v17, 0xffff0000, v17
	v_pk_mul_f32 v[16:17], v[20:21], v[16:17] op_sel_hi:[0,1]
	v_add_f32_e32 v13, 1.0, v13
	v_rcp_f32_e32 v24, v13
	v_mul_f32_e32 v13, 0xbfb8aa3b, v23
	v_exp_f32_e32 v13, v13
	s_nop 0
	v_add_f32_e32 v13, 1.0, v13
	v_rcp_f32_e32 v25, v13
	s_nop 0
	v_pk_mul_f32 v[22:23], v[24:25], v[22:23]
	s_nop 0
	v_pk_mul_f32 v[16:17], v[22:23], v[16:17]
	s_nop 0
	v_cvt_pk_bf16_f32 v13, v16, v17
	v_lshlrev_b32_e32 v16, 16, v14
	v_and_b32_e32 v17, 0xffff0000, v14
	v_mul_f32_e32 v14, 0xbfb8aa3b, v16
	v_exp_f32_e32 v14, v14
	s_nop 0
	v_add_f32_e32 v14, 1.0, v14
	v_rcp_f32_e32 v22, v14
	v_mul_f32_e32 v14, 0xbfb8aa3b, v17
	v_exp_f32_e32 v14, v14
	s_nop 0
	v_add_f32_e32 v14, 1.0, v14
	v_rcp_f32_e32 v23, v14
	s_nop 0
	v_pk_mul_f32 v[16:17], v[22:23], v[16:17]
	v_lshlrev_b32_e32 v22, 16, v18
	v_and_b32_e32 v23, 0xffff0000, v18
	v_pk_mul_f32 v[22:23], v[20:21], v[22:23] op_sel_hi:[0,1]
	v_pk_mul_f32 v[16:17], v[16:17], v[22:23]
	v_lshlrev_b32_e32 v18, 16, v19
	v_cvt_pk_bf16_f32 v14, v16, v17
	v_lshlrev_b32_e32 v16, 16, v15
	v_and_b32_e32 v17, 0xffff0000, v15
	v_mul_f32_e32 v15, 0xbfb8aa3b, v16
	v_exp_f32_e32 v15, v15
	v_and_b32_e32 v19, 0xffff0000, v19
	v_pk_mul_f32 v[18:19], v[20:21], v[18:19] op_sel_hi:[0,1]
	v_add_f32_e32 v15, 1.0, v15
	v_rcp_f32_e32 v22, v15
	v_mul_f32_e32 v15, 0xbfb8aa3b, v17
	v_exp_f32_e32 v15, v15
	s_nop 0
	v_add_f32_e32 v15, 1.0, v15
	v_rcp_f32_e32 v23, v15
	s_nop 0
	v_pk_mul_f32 v[16:17], v[22:23], v[16:17]
	s_nop 0
	v_pk_mul_f32 v[16:17], v[16:17], v[18:19]
	s_waitcnt vmcnt(14)
	v_mov_b32_e32 v8, v232
	v_mov_b32_e32 v9, v233
	v_mov_b32_e32 v10, v234
	v_mov_b32_e32 v11, v235
	v_lshlrev_b32_e32 v18, 16, v8
	v_and_b32_e32 v19, 0xffff0000, v8
	v_mul_f32_e32 v8, 0xbfb8aa3b, v18
	v_exp_f32_e32 v8, v8
	v_cvt_pk_bf16_f32 v15, v16, v17
	v_lshl_add_u64 v[16:17], v[34:35], 0, v[46:47]
	global_store_dwordx4 v[16:17], v[12:15], off
	v_add_f32_e32 v8, 1.0, v8
	v_rcp_f32_e32 v20, v8
	v_mul_f32_e32 v8, 0xbfb8aa3b, v19
	v_exp_f32_e32 v8, v8
	v_lshrrev_b32_e32 v12, 5, v48
	v_bitop3_b32 v12, v12, v48, 15 bitop3:0x6c
	v_mad_u64_u32 v[12:13], s[20:21], v12, s52, v[40:41]
	ds_read2_b64 v[12:15], v12 offset1:1
	v_add_f32_e32 v8, 1.0, v8
	v_rcp_f32_e32 v16, v21
	v_rcp_f32_e32 v21, v8
	s_nop 0
	v_pk_mul_f32 v[18:19], v[20:21], v[18:19]
	s_waitcnt lgkmcnt(0)
; #define LAS __attribute__((address_space(3)))
; __device__ __forceinline__ unsigned cvtpk(float lo, float hi) { f32x2_t v = {lo, hi}; bf16x2_t b = __builtin_convertvector(v, bf16x2_t); return __builtin_bit_cast(unsigned, b); }
; template <bool NT = false>
; __device__ __forceinline__ void final_store(const v4u (&gw)[8], LAS char* lds, bf16* yrow, int tid) {
; #pragma unroll
;     for (int it = 0; it < 8; ++it) {
;         const int tloc = (tid >> 3) + 64 * it, c = tid & 7;
;         const LAS char* row = lds + ACC_OFF + rho(tloc) * ACC_PITCH + 16 * c;
;         const v2u a0 = *(const LAS v2u*)row, a1 = *(const LAS v2u*)(row + 8);
;         const float inv = __builtin_amdgcn_rcpf(*((const LAS float*)(lds + LACC_OFF) + tloc));
;         v4u g = gw[it];
;         float gs[8];
;         { const unsigned gu[4] = {g.x, g.y, g.z, g.w};
; #pragma unroll
;           for (int k = 0; k < 4; ++k) { const float a = __builtin_bit_cast(float, gu[k] << 16), b = __builtin_bit_cast(float, gu[k] & 0xffff0000u);
;               gs[2 * k] = a * __builtin_amdgcn_rcpf(1.0f + __builtin_amdgcn_exp2f(-LOG2E * a)); gs[2 * k + 1] = b * __builtin_amdgcn_rcpf(1.0f + __builtin_amdgcn_exp2f(-LOG2E * b)); } }
;         v4u w;
;         w.x = cvtpk(__builtin_bit_cast(float, a0.x << 16) * inv * gs[0], __builtin_bit_cast(float, a0.x & 0xffff0000u) * inv * gs[1]);
;         w.y = cvtpk(__builtin_bit_cast(float, a0.y << 16) * inv * gs[2], __builtin_bit_cast(float, a0.y & 0xffff0000u) * inv * gs[3]);
;         w.z = cvtpk(__builtin_bit_cast(float, a1.x << 16) * inv * gs[4], __builtin_bit_cast(float, a1.x & 0xffff0000u) * inv * gs[5]);
;         w.w = cvtpk(__builtin_bit_cast(float, a1.y << 16) * inv * gs[6], __builtin_bit_cast(float, a1.y & 0xffff0000u) * inv * gs[7]);
;         if (NT) __builtin_nontemporal_store(w, (v4u*)(yrow + (size_t)tloc * 1024 + 8 * c)); else *(v4u*)(yrow + (size_t)tloc * 1024 + 8 * c) = w;
	v_lshlrev_b32_e32 v20, 16, v12
	v_and_b32_e32 v21, 0xffff0000, v12
	v_pk_mul_f32 v[20:21], v[16:17], v[20:21] op_sel_hi:[0,1]
	v_pk_mul_f32 v[18:19], v[18:19], v[20:21]
	v_lshlrev_b32_e32 v12, 16, v13
	v_cvt_pk_bf16_f32 v8, v18, v19
	v_lshlrev_b32_e32 v18, 16, v9
	v_and_b32_e32 v19, 0xffff0000, v9
	v_mul_f32_e32 v9, 0xbfb8aa3b, v18
	v_exp_f32_e32 v9, v9
	v_and_b32_e32 v13, 0xffff0000, v13
	v_pk_mul_f32 v[12:13], v[16:17], v[12:13] op_sel_hi:[0,1]
	v_add_f32_e32 v9, 1.0, v9
	v_rcp_f32_e32 v20, v9
	v_mul_f32_e32 v9, 0xbfb8aa3b, v19
	v_exp_f32_e32 v9, v9
	s_nop 0
	v_add_f32_e32 v9, 1.0, v9
	v_rcp_f32_e32 v21, v9
	s_nop 0
	v_pk_mul_f32 v[18:19], v[20:21], v[18:19]
	s_nop 0
	v_pk_mul_f32 v[12:13], v[18:19], v[12:13]
	s_nop 0
	v_cvt_pk_bf16_f32 v9, v12, v13
	v_lshlrev_b32_e32 v12, 16, v10
	v_and_b32_e32 v13, 0xffff0000, v10
	v_mul_f32_e32 v10, 0xbfb8aa3b, v12
	v_exp_f32_e32 v10, v10
	s_nop 0
	v_add_f32_e32 v10, 1.0, v10
	v_rcp_f32_e32 v18, v10
	v_mul_f32_e32 v10, 0xbfb8aa3b, v13
	v_exp_f32_e32 v10, v10
	s_nop 0
	v_add_f32_e32 v10, 1.0, v10
	v_rcp_f32_e32 v19, v10
	s_nop 0
	v_pk_mul_f32 v[12:13], v[18:19], v[12:13]
	v_lshlrev_b32_e32 v18, 16, v14
	v_and_b32_e32 v19, 0xffff0000, v14
	v_pk_mul_f32 v[18:19], v[16:17], v[18:19] op_sel_hi:[0,1]
	v_pk_mul_f32 v[12:13], v[12:13], v[18:19]
	v_lshlrev_b32_e32 v14, 16, v15
	v_cvt_pk_bf16_f32 v10, v12, v13
	v_lshlrev_b32_e32 v12, 16, v11
	v_and_b32_e32 v13, 0xffff0000, v11
	v_mul_f32_e32 v11, 0xbfb8aa3b, v12
	v_exp_f32_e32 v11, v11
	v_and_b32_e32 v15, 0xffff0000, v15
	v_pk_mul_f32 v[14:15], v[16:17], v[14:15] op_sel_hi:[0,1]
	v_add_f32_e32 v11, 1.0, v11
	v_rcp_f32_e32 v18, v11
	v_mul_f32_e32 v11, 0xbfb8aa3b, v13
	v_exp_f32_e32 v11, v11
	s_nop 0
	v_add_f32_e32 v11, 1.0, v11
	v_rcp_f32_e32 v19, v11
	s_nop 0
	v_pk_mul_f32 v[12:13], v[18:19], v[12:13]
	s_nop 0
	v_pk_mul_f32 v[12:13], v[12:13], v[14:15]
	s_waitcnt vmcnt(14)
	v_mov_b32_e32 v4, v236
	v_mov_b32_e32 v5, v237
	v_mov_b32_e32 v6, v238
	v_mov_b32_e32 v7, v239
	v_lshlrev_b32_e32 v14, 16, v4
	v_and_b32_e32 v15, 0xffff0000, v4
	v_mul_f32_e32 v4, 0xbfb8aa3b, v14
	v_exp_f32_e32 v4, v4
	v_cvt_pk_bf16_f32 v11, v12, v13
	v_lshl_add_u64 v[12:13], v[34:35], 0, v[42:43]
	global_store_dwordx4 v[12:13], v[8:11], off
	v_add_f32_e32 v4, 1.0, v4
	v_rcp_f32_e32 v16, v4
	v_lshrrev_b32_e32 v8, 5, v44
	v_bitop3_b32 v8, v8, v44, 15 bitop3:0x6c
	v_mul_f32_e32 v4, 0xbfb8aa3b, v15
	v_mad_u64_u32 v[8:9], s[20:21], v8, s52, v[40:41]
	v_exp_f32_e32 v4, v4
	ds_read2_b64 v[8:11], v8 offset1:1
	ds_read2st64_b32 v[12:13], v39 offset0:6 offset1:7
	v_add_f32_e32 v4, 1.0, v4
	v_rcp_f32_e32 v17, v4
	s_waitcnt lgkmcnt(0)
	v_rcp_f32_e32 v12, v12
	v_pk_mul_f32 v[14:15], v[16:17], v[14:15]
	v_lshlrev_b32_e32 v16, 16, v8
	v_and_b32_e32 v17, 0xffff0000, v8
	v_pk_mul_f32 v[16:17], v[12:13], v[16:17] op_sel_hi:[0,1]
	v_pk_mul_f32 v[14:15], v[14:15], v[16:17]
	v_lshlrev_b32_e32 v8, 16, v9
	v_cvt_pk_bf16_f32 v4, v14, v15
	v_lshlrev_b32_e32 v14, 16, v5
	v_and_b32_e32 v15, 0xffff0000, v5
	v_mul_f32_e32 v5, 0xbfb8aa3b, v14
	v_exp_f32_e32 v5, v5
	v_and_b32_e32 v9, 0xffff0000, v9
	v_pk_mul_f32 v[8:9], v[12:13], v[8:9] op_sel_hi:[0,1]
	v_add_f32_e32 v5, 1.0, v5
	v_rcp_f32_e32 v16, v5
	v_mul_f32_e32 v5, 0xbfb8aa3b, v15
	v_exp_f32_e32 v5, v5
	s_nop 0
	v_add_f32_e32 v5, 1.0, v5
	v_rcp_f32_e32 v17, v5
	s_nop 0
	v_pk_mul_f32 v[14:15], v[16:17], v[14:15]
	s_nop 0
	v_pk_mul_f32 v[8:9], v[14:15], v[8:9]
	s_nop 0
	v_cvt_pk_bf16_f32 v5, v8, v9
	v_lshlrev_b32_e32 v8, 16, v6
	v_and_b32_e32 v9, 0xffff0000, v6
	v_mul_f32_e32 v6, 0xbfb8aa3b, v8
	v_exp_f32_e32 v6, v6
	s_nop 0
	v_add_f32_e32 v6, 1.0, v6
	v_rcp_f32_e32 v14, v6
	v_mul_f32_e32 v6, 0xbfb8aa3b, v9
	v_exp_f32_e32 v6, v6
	s_nop 0
	v_add_f32_e32 v6, 1.0, v6
	v_rcp_f32_e32 v15, v6
	s_nop 0
	v_pk_mul_f32 v[8:9], v[14:15], v[8:9]
	v_lshlrev_b32_e32 v14, 16, v10
	v_and_b32_e32 v15, 0xffff0000, v10
	v_pk_mul_f32 v[14:15], v[12:13], v[14:15] op_sel_hi:[0,1]
	v_pk_mul_f32 v[8:9], v[8:9], v[14:15]
	v_lshlrev_b32_e32 v10, 16, v11
	v_cvt_pk_bf16_f32 v6, v8, v9
	v_lshlrev_b32_e32 v8, 16, v7
	v_and_b32_e32 v9, 0xffff0000, v7
	v_mul_f32_e32 v7, 0xbfb8aa3b, v8
	v_exp_f32_e32 v7, v7
	v_and_b32_e32 v11, 0xffff0000, v11
	v_pk_mul_f32 v[10:11], v[12:13], v[10:11] op_sel_hi:[0,1]
	v_add_f32_e32 v7, 1.0, v7
	v_rcp_f32_e32 v14, v7
	v_mul_f32_e32 v7, 0xbfb8aa3b, v9
	v_exp_f32_e32 v7, v7
	s_nop 0
	v_add_f32_e32 v7, 1.0, v7
	v_rcp_f32_e32 v15, v7
	s_nop 0
	v_pk_mul_f32 v[8:9], v[14:15], v[8:9]
	s_nop 0
	v_pk_mul_f32 v[8:9], v[8:9], v[10:11]
	s_waitcnt vmcnt(14)
; #define LAS __attribute__((address_space(3)))
; __device__ __forceinline__ unsigned cvtpk(float lo, float hi) { f32x2_t v = {lo, hi}; bf16x2_t b = __builtin_convertvector(v, bf16x2_t); return __builtin_bit_cast(unsigned, b); }
; template <bool NT = false>
; __device__ __forceinline__ void final_store(const v4u (&gw)[8], LAS char* lds, bf16* yrow, int tid) {
; #pragma unroll
;     for (int it = 0; it < 8; ++it) {
;         const int tloc = (tid >> 3) + 64 * it, c = tid & 7;
;         const LAS char* row = lds + ACC_OFF + rho(tloc) * ACC_PITCH + 16 * c;
;         const v2u a0 = *(const LAS v2u*)row, a1 = *(const LAS v2u*)(row + 8);
;         const float inv = __builtin_amdgcn_rcpf(*((const LAS float*)(lds + LACC_OFF) + tloc));
;         v4u g = gw[it];
;         float gs[8];
;         { const unsigned gu[4] = {g.x, g.y, g.z, g.w};
; #pragma unroll
;           for (int k = 0; k < 4; ++k) { const float a = __builtin_bit_cast(float, gu[k] << 16), b = __builtin_bit_cast(float, gu[k] & 0xffff0000u);
;               gs[2 * k] = a * __builtin_amdgcn_rcpf(1.0f + __builtin_amdgcn_exp2f(-LOG2E * a)); gs[2 * k + 1] = b * __builtin_amdgcn_rcpf(1.0f + __builtin_amdgcn_exp2f(-LOG2E * b)); } }
;         v4u w;
;         w.x = cvtpk(__builtin_bit_cast(float, a0.x << 16) * inv * gs[0], __builtin_bit_cast(float, a0.x & 0xffff0000u) * inv * gs[1]);
;         w.y = cvtpk(__builtin_bit_cast(float, a0.y << 16) * inv * gs[2], __builtin_bit_cast(float, a0.y & 0xffff0000u) * inv * gs[3]);
;         w.z = cvtpk(__builtin_bit_cast(float, a1.x << 16) * inv * gs[4], __builtin_bit_cast(float, a1.x & 0xffff0000u) * inv * gs[5]);
;         w.w = cvtpk(__builtin_bit_cast(float, a1.y << 16) * inv * gs[6], __builtin_bit_cast(float, a1.y & 0xffff0000u) * inv * gs[7]);
;         if (NT) __builtin_nontemporal_store(w, (v4u*)(yrow + (size_t)tloc * 1024 + 8 * c)); else *(v4u*)(yrow + (size_t)tloc * 1024 + 8 * c) = w;
; __device__ __forceinline__ void unit_b(UnitB& U, int u, const bf16* qkv) {
;     U.R = u & 7; U.h = (u >> 3) & 15; U.b = u >> 7;
;     const int kr0 = min(max(8 * U.R - 4, 0), 56), krl = min(max(8 * U.R + 7 - 4, 0), 56) + 7;
;     U.nrows = krl - kr0 + 1;
;     const bf16* Qb = qkv + ((size_t)(U.b * 16 + U.h) * 4096) * 64;
;     U.Kr = uniform_ptr(Qb + SECB + (size_t)kr0 * 4096); U.Vr = uniform_ptr(Qb + 2 * SECB + (size_t)kr0 * 4096);
; }
	v_mov_b32_e32 v0, v240
	v_mov_b32_e32 v1, v241
	v_mov_b32_e32 v2, v242
	v_mov_b32_e32 v3, v243
	v_lshlrev_b32_e32 v10, 16, v0
	v_and_b32_e32 v11, 0xffff0000, v0
	v_mul_f32_e32 v0, 0xbfb8aa3b, v10
	v_exp_f32_e32 v0, v0
	v_cvt_pk_bf16_f32 v7, v8, v9
	v_lshl_add_u64 v[8:9], v[34:35], 0, v[36:37]
	global_store_dwordx4 v[8:9], v[4:7], off
	v_add_f32_e32 v0, 1.0, v0
	v_rcp_f32_e32 v12, v0
	v_mul_f32_e32 v0, 0xbfb8aa3b, v11
	v_exp_f32_e32 v0, v0
	v_lshrrev_b32_e32 v4, 5, v38
	v_bitop3_b32 v4, v4, v38, 15 bitop3:0x6c
	v_mad_u64_u32 v[4:5], s[20:21], v4, s52, v[40:41]
	ds_read2_b64 v[4:7], v4 offset1:1
	v_add_f32_e32 v0, 1.0, v0
	v_rcp_f32_e32 v8, v13
	v_rcp_f32_e32 v13, v0
	s_nop 0
	v_pk_mul_f32 v[10:11], v[12:13], v[10:11]
	s_waitcnt lgkmcnt(0)
	v_lshlrev_b32_e32 v12, 16, v4
	v_and_b32_e32 v13, 0xffff0000, v4
	v_pk_mul_f32 v[12:13], v[8:9], v[12:13] op_sel_hi:[0,1]
	v_pk_mul_f32 v[10:11], v[10:11], v[12:13]
	v_lshlrev_b32_e32 v4, 16, v5
	v_cvt_pk_bf16_f32 v0, v10, v11
	v_lshlrev_b32_e32 v10, 16, v1
	v_and_b32_e32 v11, 0xffff0000, v1
	v_mul_f32_e32 v1, 0xbfb8aa3b, v10
	v_exp_f32_e32 v1, v1
	v_and_b32_e32 v5, 0xffff0000, v5
	v_pk_mul_f32 v[4:5], v[8:9], v[4:5] op_sel_hi:[0,1]
	v_add_f32_e32 v1, 1.0, v1
	v_rcp_f32_e32 v12, v1
	v_mul_f32_e32 v1, 0xbfb8aa3b, v11
	v_exp_f32_e32 v1, v1
	s_nop 0
	v_add_f32_e32 v1, 1.0, v1
	v_rcp_f32_e32 v13, v1
	s_nop 0
	v_pk_mul_f32 v[10:11], v[12:13], v[10:11]
	s_nop 0
	v_pk_mul_f32 v[4:5], v[10:11], v[4:5]
	s_nop 0
	v_cvt_pk_bf16_f32 v1, v4, v5
	v_lshlrev_b32_e32 v4, 16, v2
	v_and_b32_e32 v5, 0xffff0000, v2
	v_mul_f32_e32 v2, 0xbfb8aa3b, v4
	v_exp_f32_e32 v2, v2
	s_nop 0
	v_add_f32_e32 v2, 1.0, v2
	v_rcp_f32_e32 v10, v2
	v_mul_f32_e32 v2, 0xbfb8aa3b, v5
	v_exp_f32_e32 v2, v2
	s_nop 0
	v_add_f32_e32 v2, 1.0, v2
	v_rcp_f32_e32 v11, v2
	s_nop 0
	v_pk_mul_f32 v[4:5], v[10:11], v[4:5]
	v_lshlrev_b32_e32 v10, 16, v6
	v_and_b32_e32 v11, 0xffff0000, v6
	v_pk_mul_f32 v[10:11], v[8:9], v[10:11] op_sel_hi:[0,1]
	v_pk_mul_f32 v[4:5], v[4:5], v[10:11]
	v_lshlrev_b32_e32 v6, 16, v7
	v_cvt_pk_bf16_f32 v2, v4, v5
	v_lshlrev_b32_e32 v4, 16, v3
	v_and_b32_e32 v5, 0xffff0000, v3
	v_mul_f32_e32 v3, 0xbfb8aa3b, v4
	v_exp_f32_e32 v3, v3
	v_and_b32_e32 v7, 0xffff0000, v7
	v_pk_mul_f32 v[6:7], v[8:9], v[6:7] op_sel_hi:[0,1]
	v_add_f32_e32 v3, 1.0, v3
	v_rcp_f32_e32 v10, v3
	v_mul_f32_e32 v3, 0xbfb8aa3b, v5
	v_exp_f32_e32 v3, v3
	s_nop 0
	v_add_f32_e32 v3, 1.0, v3
	v_rcp_f32_e32 v11, v3
	s_nop 0
	v_pk_mul_f32 v[4:5], v[10:11], v[4:5]
	s_nop 0
	v_pk_mul_f32 v[4:5], v[4:5], v[6:7]
	s_nop 0
	v_cvt_pk_bf16_f32 v3, v4, v5
	v_lshl_add_u64 v[4:5], v[34:35], 0, v[32:33]
	global_store_dwordx4 v[4:5], v[0:3], off
	s_cbranch_scc1 .LBB0_638
	s_add_i32 s28, s28, 2
	s_and_b32 s2, s28, 7
	s_lshl_b32 s20, s2, 3
	s_max_u32 s21, s20, 4
	v_sub_u32_e64 v0, s20, 4 clamp
	s_or_b32 s20, s20, 3
	s_min_u32 s20, s20, 56
	s_ashr_i32 s39, s28, 7
	s_sub_i32 s20, s20, s21
	s_bfe_u32 s12, s28, 0x40003
	s_add_i32 s38, s20, 12
	s_lshl_b32 s20, s39, 4
	s_or_b32 s20, s20, s12
	s_ashr_i32 s21, s20, 31
	s_lshl_b64 s[20:21], s[20:21], 19
	s_add_u32 s20, s33, s20
	s_addc_u32 s21, s40, s21
	v_lshlrev_b32_e32 v146, 13, v0
	v_lshl_add_u64 v[0:1], s[20:21], 0, v[146:147]
	v_lshl_add_u64 v[2:3], v[0:1], 0, s[4:5]
	v_lshl_add_u64 v[0:1], v[0:1], 0, s[6:7]
	v_readfirstlane_b32 s23, v3
	v_readfirstlane_b32 s22, v2
	v_readfirstlane_b32 s25, v1
	v_readfirstlane_b32 s24, v0
	s_branch .LBB0_638
